# P4 epilogue de-serialised (all tile loads in flight, counted waits)
# speedup vs baseline: 1.0038x; 1.0038x over previous
.LBB0_416:
	v_lshl_add_u32 v150, s44, 8, v152
	v_lshl_add_u32 v148, s46, 8, v154
	v_lshlrev_b32_e32 v187, 12, v150
	v_lshlrev_b32_e32 v149, 2, v148
	v_lshl_add_u32 v187, v148, 1, v187
	v_lshlrev_b32_e32 v151, 2, v150
	global_load_dwordx4 v[158:161], v149, s[14:15] offset:0
	global_load_dwordx4 v[162:165], v149, s[14:15] offset:16
	global_load_dwordx4 v[166:169], v149, s[14:15] offset:512
	global_load_dwordx4 v[170:173], v149, s[14:15] offset:528
	s_mov_b32 s98, s18
	s_mov_b32 s99, s19
	s_nop 0
	global_load_dwordx4 v[188:191], v187, s[98:99]
	global_load_dwordx4 v[192:195], v187, s[98:99] offset:256
	global_load_dwordx4 v[174:177], v149, s[80:81] offset:0
	global_load_dwordx4 v[178:181], v149, s[80:81] offset:16
	global_load_dwordx4 v[182:185], v149, s[80:81] offset:512
	global_load_dwordx4 v[144:147], v149, s[80:81] offset:528
	s_add_u32 s98, s18, 0x10000
	s_addc_u32 s99, s19, 0
	s_nop 0
	global_load_dwordx4 v[196:199], v187, s[98:99]
	global_load_dwordx4 v[200:203], v187, s[98:99] offset:256
	s_add_u32 s98, s18, 0x20000
	s_addc_u32 s99, s19, 0
	s_nop 0
	global_load_dwordx4 v[204:207], v187, s[98:99]
	global_load_dwordx4 v[208:211], v187, s[98:99] offset:256
	s_add_u32 s98, s18, 0x30000
	s_addc_u32 s99, s19, 0
	s_nop 0
	global_load_dwordx4 v[212:215], v187, s[98:99]
	global_load_dwordx4 v[216:219], v187, s[98:99] offset:256
	s_add_u32 s98, s18, 0x80000
	s_addc_u32 s99, s19, 0
	s_nop 0
	global_load_dwordx4 v[220:223], v187, s[98:99]
	global_load_dwordx4 v[224:227], v187, s[98:99] offset:256
	s_add_u32 s98, s18, 0x90000
	s_addc_u32 s99, s19, 0
	s_nop 0
	global_load_dwordx4 v[228:231], v187, s[98:99]
	global_load_dwordx4 v[232:235], v187, s[98:99] offset:256
	s_mov_b32 s100, s18
	s_mov_b32 s101, s19
	s_waitcnt vmcnt(15)
	v_and_b32_e32 v237, 0xffff0000, v188
	v_lshlrev_b32_e32 v236, 16, v188
	v_and_b32_e32 v239, 0xffff0000, v189
	v_lshlrev_b32_e32 v238, 16, v189
	v_and_b32_e32 v241, 0xffff0000, v190
	v_lshlrev_b32_e32 v240, 16, v190
	v_and_b32_e32 v243, 0xffff0000, v191
	v_lshlrev_b32_e32 v242, 16, v191
	v_pk_fma_f32 v[124:125], v[236:237], v[158:159], v[124:125]
	v_pk_fma_f32 v[126:127], v[238:239], v[160:161], v[126:127]
	v_pk_fma_f32 v[120:121], v[240:241], v[162:163], v[120:121]
	v_pk_fma_f32 v[122:123], v[242:243], v[164:165], v[122:123]
	v_pk_mul_f32 v[244:245], v[124:125], v[124:125]
	v_pk_fma_f32 v[244:245], v[126:127], v[126:127], v[244:245]
	v_pk_fma_f32 v[244:245], v[120:121], v[120:121], v[244:245]
	v_pk_fma_f32 v[244:245], v[122:123], v[122:123], v[244:245]
	s_waitcnt vmcnt(12)
	v_pk_mul_f32 v[236:237], v[124:125], v[174:175]
	v_pk_mul_f32 v[238:239], v[126:127], v[176:177]
	v_pk_mul_f32 v[240:241], v[120:121], v[178:179]
	v_pk_mul_f32 v[242:243], v[122:123], v[180:181]
	v_cvt_pk_bf16_f32 v188, v236, v237
	v_cvt_pk_bf16_f32 v189, v238, v239
	v_cvt_pk_bf16_f32 v190, v240, v241
	v_cvt_pk_bf16_f32 v191, v242, v243
	s_nop 0
	global_store_dwordx4 v187, v[188:191], s[100:101]
	s_waitcnt vmcnt(15)
	v_and_b32_e32 v237, 0xffff0000, v192
	v_lshlrev_b32_e32 v236, 16, v192
	v_and_b32_e32 v239, 0xffff0000, v193
	v_lshlrev_b32_e32 v238, 16, v193
	v_and_b32_e32 v241, 0xffff0000, v194
	v_lshlrev_b32_e32 v240, 16, v194
	v_and_b32_e32 v243, 0xffff0000, v195
	v_lshlrev_b32_e32 v242, 16, v195
	v_pk_fma_f32 v[116:117], v[236:237], v[166:167], v[116:117]
	v_pk_fma_f32 v[118:119], v[238:239], v[168:169], v[118:119]
	v_pk_fma_f32 v[112:113], v[240:241], v[170:171], v[112:113]
	v_pk_fma_f32 v[114:115], v[242:243], v[172:173], v[114:115]
	v_pk_fma_f32 v[244:245], v[116:117], v[116:117], v[244:245]
	v_pk_fma_f32 v[244:245], v[118:119], v[118:119], v[244:245]
	v_pk_fma_f32 v[244:245], v[112:113], v[112:113], v[244:245]
	v_pk_fma_f32 v[244:245], v[114:115], v[114:115], v[244:245]
	s_waitcnt vmcnt(11)
	v_pk_mul_f32 v[236:237], v[116:117], v[182:183]
	v_pk_mul_f32 v[238:239], v[118:119], v[184:185]
	v_pk_mul_f32 v[240:241], v[112:113], v[144:145]
	v_pk_mul_f32 v[242:243], v[114:115], v[146:147]
	v_cvt_pk_bf16_f32 v192, v236, v237
	v_cvt_pk_bf16_f32 v193, v238, v239
	v_cvt_pk_bf16_f32 v194, v240, v241
	v_cvt_pk_bf16_f32 v195, v242, v243
	s_nop 0
	global_store_dwordx4 v187, v[192:195], s[100:101] offset:256
	v_add_f32_e32 v246, v244, v245
	s_add_u32 s98, s18, 0xa0000
	s_addc_u32 s99, s19, 0
	s_nop 0
	global_load_dwordx4 v[112:115], v187, s[98:99]
	global_load_dwordx4 v[116:119], v187, s[98:99] offset:256
	s_add_u32 s100, s18, 0x10000
	s_addc_u32 s101, s19, 0
	s_waitcnt vmcnt(13)
	v_and_b32_e32 v237, 0xffff0000, v196
	v_lshlrev_b32_e32 v236, 16, v196
	v_and_b32_e32 v239, 0xffff0000, v197
	v_lshlrev_b32_e32 v238, 16, v197
	v_and_b32_e32 v241, 0xffff0000, v198
	v_lshlrev_b32_e32 v240, 16, v198
	v_and_b32_e32 v243, 0xffff0000, v199
	v_lshlrev_b32_e32 v242, 16, v199
	v_pk_fma_f32 v[108:109], v[236:237], v[158:159], v[108:109]
	v_pk_fma_f32 v[110:111], v[238:239], v[160:161], v[110:111]
	v_pk_fma_f32 v[104:105], v[240:241], v[162:163], v[104:105]
	v_pk_fma_f32 v[106:107], v[242:243], v[164:165], v[106:107]
	v_pk_mul_f32 v[244:245], v[108:109], v[108:109]
	v_pk_fma_f32 v[244:245], v[110:111], v[110:111], v[244:245]
	v_pk_fma_f32 v[244:245], v[104:105], v[104:105], v[244:245]
	v_pk_fma_f32 v[244:245], v[106:107], v[106:107], v[244:245]
	v_pk_mul_f32 v[236:237], v[108:109], v[174:175]
	v_pk_mul_f32 v[238:239], v[110:111], v[176:177]
	v_pk_mul_f32 v[240:241], v[104:105], v[178:179]
	v_pk_mul_f32 v[242:243], v[106:107], v[180:181]
	v_cvt_pk_bf16_f32 v196, v236, v237
	v_cvt_pk_bf16_f32 v197, v238, v239
	v_cvt_pk_bf16_f32 v198, v240, v241
	v_cvt_pk_bf16_f32 v199, v242, v243
	s_nop 0
	global_store_dwordx4 v187, v[196:199], s[100:101]
	s_waitcnt vmcnt(13)
	v_and_b32_e32 v237, 0xffff0000, v200
	v_lshlrev_b32_e32 v236, 16, v200
	v_and_b32_e32 v239, 0xffff0000, v201
	v_lshlrev_b32_e32 v238, 16, v201
	v_and_b32_e32 v241, 0xffff0000, v202
	v_lshlrev_b32_e32 v240, 16, v202
	v_and_b32_e32 v243, 0xffff0000, v203
	v_lshlrev_b32_e32 v242, 16, v203
	v_pk_fma_f32 v[100:101], v[236:237], v[166:167], v[100:101]
	v_pk_fma_f32 v[102:103], v[238:239], v[168:169], v[102:103]
	v_pk_fma_f32 v[96:97], v[240:241], v[170:171], v[96:97]
	v_pk_fma_f32 v[98:99], v[242:243], v[172:173], v[98:99]
	v_pk_fma_f32 v[244:245], v[100:101], v[100:101], v[244:245]
	v_pk_fma_f32 v[244:245], v[102:103], v[102:103], v[244:245]
	v_pk_fma_f32 v[244:245], v[96:97], v[96:97], v[244:245]
	v_pk_fma_f32 v[244:245], v[98:99], v[98:99], v[244:245]
	v_pk_mul_f32 v[236:237], v[100:101], v[182:183]
	v_pk_mul_f32 v[238:239], v[102:103], v[184:185]
	v_pk_mul_f32 v[240:241], v[96:97], v[144:145]
	v_pk_mul_f32 v[242:243], v[98:99], v[146:147]
	v_cvt_pk_bf16_f32 v200, v236, v237
	v_cvt_pk_bf16_f32 v201, v238, v239
	v_cvt_pk_bf16_f32 v202, v240, v241
	v_cvt_pk_bf16_f32 v203, v242, v243
	s_nop 0
	global_store_dwordx4 v187, v[200:203], s[100:101] offset:256
	v_add_f32_e32 v247, v244, v245
	s_add_u32 s98, s18, 0xb0000
	s_addc_u32 s99, s19, 0
	s_nop 0
	global_load_dwordx4 v[96:99], v187, s[98:99]
	global_load_dwordx4 v[100:103], v187, s[98:99] offset:256
	s_add_u32 s100, s18, 0x20000
	s_addc_u32 s101, s19, 0
	s_waitcnt vmcnt(15)
	v_and_b32_e32 v237, 0xffff0000, v204
	v_lshlrev_b32_e32 v236, 16, v204
	v_and_b32_e32 v239, 0xffff0000, v205
	v_lshlrev_b32_e32 v238, 16, v205
	v_and_b32_e32 v241, 0xffff0000, v206
	v_lshlrev_b32_e32 v240, 16, v206
	v_and_b32_e32 v243, 0xffff0000, v207
	v_lshlrev_b32_e32 v242, 16, v207
	v_pk_fma_f32 v[92:93], v[236:237], v[158:159], v[92:93]
	v_pk_fma_f32 v[94:95], v[238:239], v[160:161], v[94:95]
	v_pk_fma_f32 v[88:89], v[240:241], v[162:163], v[88:89]
	v_pk_fma_f32 v[90:91], v[242:243], v[164:165], v[90:91]
	v_pk_mul_f32 v[244:245], v[92:93], v[92:93]
	v_pk_fma_f32 v[244:245], v[94:95], v[94:95], v[244:245]
	v_pk_fma_f32 v[244:245], v[88:89], v[88:89], v[244:245]
	v_pk_fma_f32 v[244:245], v[90:91], v[90:91], v[244:245]
	v_pk_mul_f32 v[236:237], v[92:93], v[174:175]
	v_pk_mul_f32 v[238:239], v[94:95], v[176:177]
	v_pk_mul_f32 v[240:241], v[88:89], v[178:179]
	v_pk_mul_f32 v[242:243], v[90:91], v[180:181]
	v_cvt_pk_bf16_f32 v204, v236, v237
	v_cvt_pk_bf16_f32 v205, v238, v239
	v_cvt_pk_bf16_f32 v206, v240, v241
	v_cvt_pk_bf16_f32 v207, v242, v243
	s_nop 0
	global_store_dwordx4 v187, v[204:207], s[100:101]
	s_waitcnt vmcnt(15)
	v_and_b32_e32 v237, 0xffff0000, v208
	v_lshlrev_b32_e32 v236, 16, v208
	v_and_b32_e32 v239, 0xffff0000, v209
	v_lshlrev_b32_e32 v238, 16, v209
	v_and_b32_e32 v241, 0xffff0000, v210
	v_lshlrev_b32_e32 v240, 16, v210
	v_and_b32_e32 v243, 0xffff0000, v211
	v_lshlrev_b32_e32 v242, 16, v211
	v_pk_fma_f32 v[84:85], v[236:237], v[166:167], v[84:85]
	v_pk_fma_f32 v[86:87], v[238:239], v[168:169], v[86:87]
	v_pk_fma_f32 v[80:81], v[240:241], v[170:171], v[80:81]
	v_pk_fma_f32 v[82:83], v[242:243], v[172:173], v[82:83]
	v_pk_fma_f32 v[244:245], v[84:85], v[84:85], v[244:245]
	v_pk_fma_f32 v[244:245], v[86:87], v[86:87], v[244:245]
	v_pk_fma_f32 v[244:245], v[80:81], v[80:81], v[244:245]
	v_pk_fma_f32 v[244:245], v[82:83], v[82:83], v[244:245]
	v_pk_mul_f32 v[236:237], v[84:85], v[182:183]
	v_pk_mul_f32 v[238:239], v[86:87], v[184:185]
	v_pk_mul_f32 v[240:241], v[80:81], v[144:145]
	v_pk_mul_f32 v[242:243], v[82:83], v[146:147]
	v_cvt_pk_bf16_f32 v208, v236, v237
	v_cvt_pk_bf16_f32 v209, v238, v239
	v_cvt_pk_bf16_f32 v210, v240, v241
	v_cvt_pk_bf16_f32 v211, v242, v243
	s_nop 0
	global_store_dwordx4 v187, v[208:211], s[100:101] offset:256
	v_add_f32_e32 v248, v244, v245
	s_add_u32 s100, s18, 0x30000
	s_addc_u32 s101, s19, 0
	s_waitcnt vmcnt(15)
	v_and_b32_e32 v237, 0xffff0000, v212
	v_lshlrev_b32_e32 v236, 16, v212
	v_and_b32_e32 v239, 0xffff0000, v213
	v_lshlrev_b32_e32 v238, 16, v213
	v_and_b32_e32 v241, 0xffff0000, v214
	v_lshlrev_b32_e32 v240, 16, v214
	v_and_b32_e32 v243, 0xffff0000, v215
	v_lshlrev_b32_e32 v242, 16, v215
	v_pk_fma_f32 v[76:77], v[236:237], v[158:159], v[76:77]
	v_pk_fma_f32 v[78:79], v[238:239], v[160:161], v[78:79]
	v_pk_fma_f32 v[72:73], v[240:241], v[162:163], v[72:73]
	v_pk_fma_f32 v[74:75], v[242:243], v[164:165], v[74:75]
	v_pk_mul_f32 v[244:245], v[76:77], v[76:77]
	v_pk_fma_f32 v[244:245], v[78:79], v[78:79], v[244:245]
	v_pk_fma_f32 v[244:245], v[72:73], v[72:73], v[244:245]
	v_pk_fma_f32 v[244:245], v[74:75], v[74:75], v[244:245]
	v_pk_mul_f32 v[236:237], v[76:77], v[174:175]
	v_pk_mul_f32 v[238:239], v[78:79], v[176:177]
	v_pk_mul_f32 v[240:241], v[72:73], v[178:179]
	v_pk_mul_f32 v[242:243], v[74:75], v[180:181]
	v_cvt_pk_bf16_f32 v212, v236, v237
	v_cvt_pk_bf16_f32 v213, v238, v239
	v_cvt_pk_bf16_f32 v214, v240, v241
	v_cvt_pk_bf16_f32 v215, v242, v243
	s_nop 0
	global_store_dwordx4 v187, v[212:215], s[100:101]
	s_waitcnt vmcnt(15)
	v_and_b32_e32 v237, 0xffff0000, v216
	v_lshlrev_b32_e32 v236, 16, v216
	v_and_b32_e32 v239, 0xffff0000, v217
	v_lshlrev_b32_e32 v238, 16, v217
	v_and_b32_e32 v241, 0xffff0000, v218
	v_lshlrev_b32_e32 v240, 16, v218
	v_and_b32_e32 v243, 0xffff0000, v219
	v_lshlrev_b32_e32 v242, 16, v219
	v_pk_fma_f32 v[68:69], v[236:237], v[166:167], v[68:69]
	v_pk_fma_f32 v[70:71], v[238:239], v[168:169], v[70:71]
	v_pk_fma_f32 v[64:65], v[240:241], v[170:171], v[64:65]
	v_pk_fma_f32 v[66:67], v[242:243], v[172:173], v[66:67]
	v_pk_fma_f32 v[244:245], v[68:69], v[68:69], v[244:245]
	v_pk_fma_f32 v[244:245], v[70:71], v[70:71], v[244:245]
	v_pk_fma_f32 v[244:245], v[64:65], v[64:65], v[244:245]
	v_pk_fma_f32 v[244:245], v[66:67], v[66:67], v[244:245]
	v_pk_mul_f32 v[236:237], v[68:69], v[182:183]
	v_pk_mul_f32 v[238:239], v[70:71], v[184:185]
	v_pk_mul_f32 v[240:241], v[64:65], v[144:145]
	v_pk_mul_f32 v[242:243], v[66:67], v[146:147]
	v_cvt_pk_bf16_f32 v216, v236, v237
	v_cvt_pk_bf16_f32 v217, v238, v239
	v_cvt_pk_bf16_f32 v218, v240, v241
	v_cvt_pk_bf16_f32 v219, v242, v243
	s_nop 0
	global_store_dwordx4 v187, v[216:219], s[100:101] offset:256
	v_add_f32_e32 v249, v244, v245
	s_add_u32 s100, s18, 0x80000
	s_addc_u32 s101, s19, 0
	s_waitcnt vmcnt(15)
	v_and_b32_e32 v237, 0xffff0000, v220
	v_lshlrev_b32_e32 v236, 16, v220
	v_and_b32_e32 v239, 0xffff0000, v221
	v_lshlrev_b32_e32 v238, 16, v221
	v_and_b32_e32 v241, 0xffff0000, v222
	v_lshlrev_b32_e32 v240, 16, v222
	v_and_b32_e32 v243, 0xffff0000, v223
	v_lshlrev_b32_e32 v242, 16, v223
	v_pk_fma_f32 v[60:61], v[236:237], v[158:159], v[60:61]
	v_pk_fma_f32 v[62:63], v[238:239], v[160:161], v[62:63]
	v_pk_fma_f32 v[56:57], v[240:241], v[162:163], v[56:57]
	v_pk_fma_f32 v[58:59], v[242:243], v[164:165], v[58:59]
	v_pk_mul_f32 v[244:245], v[60:61], v[60:61]
	v_pk_fma_f32 v[244:245], v[62:63], v[62:63], v[244:245]
	v_pk_fma_f32 v[244:245], v[56:57], v[56:57], v[244:245]
	v_pk_fma_f32 v[244:245], v[58:59], v[58:59], v[244:245]
	v_pk_mul_f32 v[236:237], v[60:61], v[174:175]
	v_pk_mul_f32 v[238:239], v[62:63], v[176:177]
	v_pk_mul_f32 v[240:241], v[56:57], v[178:179]
	v_pk_mul_f32 v[242:243], v[58:59], v[180:181]
	v_cvt_pk_bf16_f32 v220, v236, v237
	v_cvt_pk_bf16_f32 v221, v238, v239
	v_cvt_pk_bf16_f32 v222, v240, v241
	v_cvt_pk_bf16_f32 v223, v242, v243
	s_nop 0
	global_store_dwordx4 v187, v[220:223], s[100:101]
	s_waitcnt vmcnt(15)
	v_and_b32_e32 v237, 0xffff0000, v224
	v_lshlrev_b32_e32 v236, 16, v224
	v_and_b32_e32 v239, 0xffff0000, v225
	v_lshlrev_b32_e32 v238, 16, v225
	v_and_b32_e32 v241, 0xffff0000, v226
	v_lshlrev_b32_e32 v240, 16, v226
	v_and_b32_e32 v243, 0xffff0000, v227
	v_lshlrev_b32_e32 v242, 16, v227
	v_pk_fma_f32 v[52:53], v[236:237], v[166:167], v[52:53]
	v_pk_fma_f32 v[54:55], v[238:239], v[168:169], v[54:55]
	v_pk_fma_f32 v[48:49], v[240:241], v[170:171], v[48:49]
	v_pk_fma_f32 v[50:51], v[242:243], v[172:173], v[50:51]
	v_pk_fma_f32 v[244:245], v[52:53], v[52:53], v[244:245]
	v_pk_fma_f32 v[244:245], v[54:55], v[54:55], v[244:245]
	v_pk_fma_f32 v[244:245], v[48:49], v[48:49], v[244:245]
	v_pk_fma_f32 v[244:245], v[50:51], v[50:51], v[244:245]
	v_pk_mul_f32 v[236:237], v[52:53], v[182:183]
	v_pk_mul_f32 v[238:239], v[54:55], v[184:185]
	v_pk_mul_f32 v[240:241], v[48:49], v[144:145]
	v_pk_mul_f32 v[242:243], v[50:51], v[146:147]
	v_cvt_pk_bf16_f32 v224, v236, v237
	v_cvt_pk_bf16_f32 v225, v238, v239
	v_cvt_pk_bf16_f32 v226, v240, v241
	v_cvt_pk_bf16_f32 v227, v242, v243
	s_nop 0
	global_store_dwordx4 v187, v[224:227], s[100:101] offset:256
	v_add_f32_e32 v250, v244, v245
	s_add_u32 s100, s18, 0x90000
	s_addc_u32 s101, s19, 0
	s_waitcnt vmcnt(15)
	v_and_b32_e32 v237, 0xffff0000, v228
	v_lshlrev_b32_e32 v236, 16, v228
	v_and_b32_e32 v239, 0xffff0000, v229
	v_lshlrev_b32_e32 v238, 16, v229
	v_and_b32_e32 v241, 0xffff0000, v230
	v_lshlrev_b32_e32 v240, 16, v230
	v_and_b32_e32 v243, 0xffff0000, v231
	v_lshlrev_b32_e32 v242, 16, v231
	v_pk_fma_f32 v[44:45], v[236:237], v[158:159], v[44:45]
	v_pk_fma_f32 v[46:47], v[238:239], v[160:161], v[46:47]
	v_pk_fma_f32 v[40:41], v[240:241], v[162:163], v[40:41]
	v_pk_fma_f32 v[42:43], v[242:243], v[164:165], v[42:43]
	v_pk_mul_f32 v[244:245], v[44:45], v[44:45]
	v_pk_fma_f32 v[244:245], v[46:47], v[46:47], v[244:245]
	v_pk_fma_f32 v[244:245], v[40:41], v[40:41], v[244:245]
	v_pk_fma_f32 v[244:245], v[42:43], v[42:43], v[244:245]
	v_pk_mul_f32 v[236:237], v[44:45], v[174:175]
	v_pk_mul_f32 v[238:239], v[46:47], v[176:177]
	v_pk_mul_f32 v[240:241], v[40:41], v[178:179]
	v_pk_mul_f32 v[242:243], v[42:43], v[180:181]
	v_cvt_pk_bf16_f32 v228, v236, v237
	v_cvt_pk_bf16_f32 v229, v238, v239
	v_cvt_pk_bf16_f32 v230, v240, v241
	v_cvt_pk_bf16_f32 v231, v242, v243
	s_nop 0
	global_store_dwordx4 v187, v[228:231], s[100:101]
	s_waitcnt vmcnt(15)
	v_and_b32_e32 v237, 0xffff0000, v232
	v_lshlrev_b32_e32 v236, 16, v232
	v_and_b32_e32 v239, 0xffff0000, v233
	v_lshlrev_b32_e32 v238, 16, v233
	v_and_b32_e32 v241, 0xffff0000, v234
	v_lshlrev_b32_e32 v240, 16, v234
	v_and_b32_e32 v243, 0xffff0000, v235
	v_lshlrev_b32_e32 v242, 16, v235
	v_pk_fma_f32 v[36:37], v[236:237], v[166:167], v[36:37]
	v_pk_fma_f32 v[38:39], v[238:239], v[168:169], v[38:39]
	v_pk_fma_f32 v[32:33], v[240:241], v[170:171], v[32:33]
	v_pk_fma_f32 v[34:35], v[242:243], v[172:173], v[34:35]
	v_pk_fma_f32 v[244:245], v[36:37], v[36:37], v[244:245]
	v_pk_fma_f32 v[244:245], v[38:39], v[38:39], v[244:245]
	v_pk_fma_f32 v[244:245], v[32:33], v[32:33], v[244:245]
	v_pk_fma_f32 v[244:245], v[34:35], v[34:35], v[244:245]
	v_pk_mul_f32 v[236:237], v[36:37], v[182:183]
	v_pk_mul_f32 v[238:239], v[38:39], v[184:185]
	v_pk_mul_f32 v[240:241], v[32:33], v[144:145]
	v_pk_mul_f32 v[242:243], v[34:35], v[146:147]
	v_cvt_pk_bf16_f32 v232, v236, v237
	v_cvt_pk_bf16_f32 v233, v238, v239
	v_cvt_pk_bf16_f32 v234, v240, v241
	v_cvt_pk_bf16_f32 v235, v242, v243
	s_nop 0
	global_store_dwordx4 v187, v[232:235], s[100:101] offset:256
	v_add_f32_e32 v251, v244, v245
	s_add_u32 s100, s18, 0xa0000
	s_addc_u32 s101, s19, 0
	s_waitcnt vmcnt(13)
	v_and_b32_e32 v237, 0xffff0000, v112
	v_lshlrev_b32_e32 v236, 16, v112
	v_and_b32_e32 v239, 0xffff0000, v113
	v_lshlrev_b32_e32 v238, 16, v113
	v_and_b32_e32 v241, 0xffff0000, v114
	v_lshlrev_b32_e32 v240, 16, v114
	v_and_b32_e32 v243, 0xffff0000, v115
	v_lshlrev_b32_e32 v242, 16, v115
	v_pk_fma_f32 v[28:29], v[236:237], v[158:159], v[28:29]
	v_pk_fma_f32 v[30:31], v[238:239], v[160:161], v[30:31]
	v_pk_fma_f32 v[24:25], v[240:241], v[162:163], v[24:25]
	v_pk_fma_f32 v[26:27], v[242:243], v[164:165], v[26:27]
	v_pk_mul_f32 v[244:245], v[28:29], v[28:29]
	v_pk_fma_f32 v[244:245], v[30:31], v[30:31], v[244:245]
	v_pk_fma_f32 v[244:245], v[24:25], v[24:25], v[244:245]
	v_pk_fma_f32 v[244:245], v[26:27], v[26:27], v[244:245]
	v_pk_mul_f32 v[236:237], v[28:29], v[174:175]
	v_pk_mul_f32 v[238:239], v[30:31], v[176:177]
	v_pk_mul_f32 v[240:241], v[24:25], v[178:179]
	v_pk_mul_f32 v[242:243], v[26:27], v[180:181]
	v_cvt_pk_bf16_f32 v112, v236, v237
	v_cvt_pk_bf16_f32 v113, v238, v239
	v_cvt_pk_bf16_f32 v114, v240, v241
	v_cvt_pk_bf16_f32 v115, v242, v243
	s_nop 0
	global_store_dwordx4 v187, v[112:115], s[100:101]
	s_waitcnt vmcnt(13)
	v_and_b32_e32 v237, 0xffff0000, v116
	v_lshlrev_b32_e32 v236, 16, v116
	v_and_b32_e32 v239, 0xffff0000, v117
	v_lshlrev_b32_e32 v238, 16, v117
	v_and_b32_e32 v241, 0xffff0000, v118
	v_lshlrev_b32_e32 v240, 16, v118
	v_and_b32_e32 v243, 0xffff0000, v119
	v_lshlrev_b32_e32 v242, 16, v119
	v_pk_fma_f32 v[20:21], v[236:237], v[166:167], v[20:21]
	v_pk_fma_f32 v[22:23], v[238:239], v[168:169], v[22:23]
	v_pk_fma_f32 v[16:17], v[240:241], v[170:171], v[16:17]
	v_pk_fma_f32 v[18:19], v[242:243], v[172:173], v[18:19]
	v_pk_fma_f32 v[244:245], v[20:21], v[20:21], v[244:245]
	v_pk_fma_f32 v[244:245], v[22:23], v[22:23], v[244:245]
	v_pk_fma_f32 v[244:245], v[16:17], v[16:17], v[244:245]
	v_pk_fma_f32 v[244:245], v[18:19], v[18:19], v[244:245]
	v_pk_mul_f32 v[236:237], v[20:21], v[182:183]
	v_pk_mul_f32 v[238:239], v[22:23], v[184:185]
	v_pk_mul_f32 v[240:241], v[16:17], v[144:145]
	v_pk_mul_f32 v[242:243], v[18:19], v[146:147]
	v_cvt_pk_bf16_f32 v116, v236, v237
	v_cvt_pk_bf16_f32 v117, v238, v239
	v_cvt_pk_bf16_f32 v118, v240, v241
	v_cvt_pk_bf16_f32 v119, v242, v243
	s_nop 0
	global_store_dwordx4 v187, v[116:119], s[100:101] offset:256
	v_add_f32_e32 v252, v244, v245
	s_add_u32 s100, s18, 0xb0000
	s_addc_u32 s101, s19, 0
	s_waitcnt vmcnt(11)
	v_and_b32_e32 v237, 0xffff0000, v96
	v_lshlrev_b32_e32 v236, 16, v96
	v_and_b32_e32 v239, 0xffff0000, v97
	v_lshlrev_b32_e32 v238, 16, v97
	v_and_b32_e32 v241, 0xffff0000, v98
	v_lshlrev_b32_e32 v240, 16, v98
	v_and_b32_e32 v243, 0xffff0000, v99
	v_lshlrev_b32_e32 v242, 16, v99
	v_pk_fma_f32 v[12:13], v[236:237], v[158:159], v[12:13]
	v_pk_fma_f32 v[14:15], v[238:239], v[160:161], v[14:15]
	v_pk_fma_f32 v[8:9], v[240:241], v[162:163], v[8:9]
	v_pk_fma_f32 v[10:11], v[242:243], v[164:165], v[10:11]
	v_pk_mul_f32 v[244:245], v[12:13], v[12:13]
	v_pk_fma_f32 v[244:245], v[14:15], v[14:15], v[244:245]
	v_pk_fma_f32 v[244:245], v[8:9], v[8:9], v[244:245]
	v_pk_fma_f32 v[244:245], v[10:11], v[10:11], v[244:245]
	v_pk_mul_f32 v[236:237], v[12:13], v[174:175]
	v_pk_mul_f32 v[238:239], v[14:15], v[176:177]
	v_pk_mul_f32 v[240:241], v[8:9], v[178:179]
	v_pk_mul_f32 v[242:243], v[10:11], v[180:181]
	v_cvt_pk_bf16_f32 v96, v236, v237
	v_cvt_pk_bf16_f32 v97, v238, v239
	v_cvt_pk_bf16_f32 v98, v240, v241
	v_cvt_pk_bf16_f32 v99, v242, v243
	s_nop 0
	global_store_dwordx4 v187, v[96:99], s[100:101]
	s_waitcnt vmcnt(11)
	v_and_b32_e32 v237, 0xffff0000, v100
	v_lshlrev_b32_e32 v236, 16, v100
	v_and_b32_e32 v239, 0xffff0000, v101
	v_lshlrev_b32_e32 v238, 16, v101
	v_and_b32_e32 v241, 0xffff0000, v102
	v_lshlrev_b32_e32 v240, 16, v102
	v_and_b32_e32 v243, 0xffff0000, v103
	v_lshlrev_b32_e32 v242, 16, v103
	v_pk_fma_f32 v[4:5], v[236:237], v[166:167], v[4:5]
	v_pk_fma_f32 v[6:7], v[238:239], v[168:169], v[6:7]
	v_pk_fma_f32 v[0:1], v[240:241], v[170:171], v[0:1]
	v_pk_fma_f32 v[2:3], v[242:243], v[172:173], v[2:3]
	v_pk_fma_f32 v[244:245], v[4:5], v[4:5], v[244:245]
	v_pk_fma_f32 v[244:245], v[6:7], v[6:7], v[244:245]
	v_pk_fma_f32 v[244:245], v[0:1], v[0:1], v[244:245]
	v_pk_fma_f32 v[244:245], v[2:3], v[2:3], v[244:245]
	v_pk_mul_f32 v[236:237], v[4:5], v[182:183]
	v_pk_mul_f32 v[238:239], v[6:7], v[184:185]
	v_pk_mul_f32 v[240:241], v[0:1], v[144:145]
	v_pk_mul_f32 v[242:243], v[2:3], v[146:147]
	v_cvt_pk_bf16_f32 v100, v236, v237
	v_cvt_pk_bf16_f32 v101, v238, v239
	v_cvt_pk_bf16_f32 v102, v240, v241
	v_cvt_pk_bf16_f32 v103, v242, v243
	s_nop 0
	global_store_dwordx4 v187, v[100:103], s[100:101] offset:256
	v_add_f32_e32 v253, v244, v245
	v_xor_b32_e32 v236, 16, v186
	v_xor_b32_e32 v237, 32, v186
	v_lshlrev_b32_e32 v236, 2, v236
	v_lshlrev_b32_e32 v237, 2, v237
	ds_bpermute_b32 v120, v236, v246
	ds_bpermute_b32 v121, v236, v247
	ds_bpermute_b32 v122, v236, v248
	ds_bpermute_b32 v123, v236, v249
	ds_bpermute_b32 v124, v236, v250
	ds_bpermute_b32 v125, v236, v251
	ds_bpermute_b32 v126, v236, v252
	ds_bpermute_b32 v127, v236, v253
	s_waitcnt lgkmcnt(7)
	v_add_f32_e32 v246, v246, v120
	s_waitcnt lgkmcnt(6)
	v_add_f32_e32 v247, v247, v121
	s_waitcnt lgkmcnt(5)
	v_add_f32_e32 v248, v248, v122
	s_waitcnt lgkmcnt(4)
	v_add_f32_e32 v249, v249, v123
	s_waitcnt lgkmcnt(3)
	v_add_f32_e32 v250, v250, v124
	s_waitcnt lgkmcnt(2)
	v_add_f32_e32 v251, v251, v125
	s_waitcnt lgkmcnt(1)
	v_add_f32_e32 v252, v252, v126
	s_waitcnt lgkmcnt(0)
	v_add_f32_e32 v253, v253, v127
	ds_bpermute_b32 v120, v237, v246
	ds_bpermute_b32 v121, v237, v247
	ds_bpermute_b32 v122, v237, v248
	ds_bpermute_b32 v123, v237, v249
	ds_bpermute_b32 v124, v237, v250
	ds_bpermute_b32 v125, v237, v251
	ds_bpermute_b32 v126, v237, v252
	ds_bpermute_b32 v127, v237, v253
	s_and_saveexec_b64 s[44:45], s[4:5]
	s_waitcnt lgkmcnt(7)
	v_add_f32_e32 v246, v246, v120
	global_atomic_add_f32 v151, v246, s[12:13]
	s_waitcnt lgkmcnt(6)
	v_add_f32_e32 v247, v247, v121
	global_atomic_add_f32 v151, v247, s[12:13] offset:64
	s_waitcnt lgkmcnt(5)
	v_add_f32_e32 v248, v248, v122
	global_atomic_add_f32 v151, v248, s[12:13] offset:128
	s_waitcnt lgkmcnt(4)
	v_add_f32_e32 v249, v249, v123
	global_atomic_add_f32 v151, v249, s[12:13] offset:192
	s_waitcnt lgkmcnt(3)
	v_add_f32_e32 v250, v250, v124
	global_atomic_add_f32 v151, v250, s[12:13] offset:512
	s_waitcnt lgkmcnt(2)
	v_add_f32_e32 v251, v251, v125
	global_atomic_add_f32 v151, v251, s[12:13] offset:576
	s_waitcnt lgkmcnt(1)
	v_add_f32_e32 v252, v252, v126
	global_atomic_add_f32 v151, v252, s[12:13] offset:640
	s_waitcnt lgkmcnt(0)
	v_add_f32_e32 v253, v253, v127
	global_atomic_add_f32 v151, v253, s[12:13] offset:704

	.amdhsa_kernel _Z14fwd_megakernel4Args
		.amdhsa_group_segment_fixed_size 0
		.amdhsa_private_segment_fixed_size 0
		.amdhsa_kernarg_size 368
		.amdhsa_user_sgpr_count 2
		.amdhsa_user_sgpr_dispatch_ptr 0
		.amdhsa_user_sgpr_queue_ptr 0
		.amdhsa_user_sgpr_kernarg_segment_ptr 1
		.amdhsa_user_sgpr_dispatch_id 0
		.amdhsa_user_sgpr_kernarg_preload_length 0
		.amdhsa_user_sgpr_kernarg_preload_offset 0
		.amdhsa_user_sgpr_private_segment_size 0
		.amdhsa_uses_dynamic_stack 0
		.amdhsa_enable_private_segment 0
		.amdhsa_system_sgpr_workgroup_id_x 1
		.amdhsa_system_sgpr_workgroup_id_y 0
		.amdhsa_system_sgpr_workgroup_id_z 0
		.amdhsa_system_sgpr_workgroup_info 0
		.amdhsa_system_vgpr_workitem_id 2
		.amdhsa_next_free_vgpr 255
		.amdhsa_next_free_sgpr 102
		.amdhsa_accum_offset 256
		.amdhsa_reserve_vcc 1
		.amdhsa_float_round_mode_32 0
		.amdhsa_float_round_mode_16_64 0
		.amdhsa_float_denorm_mode_32 3
		.amdhsa_float_denorm_mode_16_64 3
		.amdhsa_dx10_clamp 1
		.amdhsa_ieee_mode 1
		.amdhsa_fp16_overflow 0
		.amdhsa_tg_split 0
		.amdhsa_exception_fp_ieee_invalid_op 0
		.amdhsa_exception_fp_denorm_src 0
		.amdhsa_exception_fp_ieee_div_zero 0
		.amdhsa_exception_fp_ieee_overflow 0
		.amdhsa_exception_fp_ieee_underflow 0
		.amdhsa_exception_fp_ieee_inexact 0
		.amdhsa_exception_int_div_zero 0
	.end_amdhsa_kernel

amdhsa.kernels:
  - .agpr_count:     0
    .args:
      - .offset:         0
        .size:           112
        .value_kind:     by_value
      - .offset:         112
        .size:           4
        .value_kind:     hidden_block_count_x
      - .offset:         116
        .size:           4
        .value_kind:     hidden_block_count_y
      - .offset:         120
        .size:           4
        .value_kind:     hidden_block_count_z
      - .offset:         124
        .size:           2
        .value_kind:     hidden_group_size_x
      - .offset:         126
        .size:           2
        .value_kind:     hidden_group_size_y
      - .offset:         128
        .size:           2
        .value_kind:     hidden_group_size_z
      - .offset:         130
        .size:           2
        .value_kind:     hidden_remainder_x
      - .offset:         132
        .size:           2
        .value_kind:     hidden_remainder_y
      - .offset:         134
        .size:           2
        .value_kind:     hidden_remainder_z
      - .offset:         152
        .size:           8
        .value_kind:     hidden_global_offset_x
      - .offset:         160
        .size:           8
        .value_kind:     hidden_global_offset_y
      - .offset:         168
        .size:           8
        .value_kind:     hidden_global_offset_z
      - .offset:         176
        .size:           2
        .value_kind:     hidden_grid_dims
      - .offset:         200
        .size:           8
        .value_kind:     hidden_multigrid_sync_arg
      - .offset:         232
        .size:           4
        .value_kind:     hidden_dynamic_lds_size
    .group_segment_fixed_size: 0
    .kernarg_segment_align: 8
    .kernarg_segment_size: 368
    .language:       OpenCL C
    .language_version:
      - 2
      - 0
    .max_flat_workgroup_size: 512
    .name:           _Z14fwd_megakernel4Args
    .private_segment_fixed_size: 0
    .sgpr_count:     108
    .sgpr_spill_count: 38
    .symbol:         _Z14fwd_megakernel4Args.kd
    .uniform_work_group_size: 1
    .uses_dynamic_stack: false
    .vgpr_count:     255
    .vgpr_spill_count: 0
    .wavefront_size: 64
